# speedup vs baseline: 1.0099x; 1.0099x over previous
; #define LAS __attribute__((address_space(3)))
; __device__ __forceinline__ float bflo(unsigned w) { return __uint_as_float(w << 16); }
; __device__ __forceinline__ float bfhi(unsigned w) { return __uint_as_float(w & 0xffff0000u); }
; __device__ __forceinline__ void mixer_phase(LAS unsigned char* lds, const u16* z, u16* zg, u16* ya, const float* lbp, const u16* bbt, const u16* cm, const float* Dp,
;                                             const float* cw, const float* cb, int bid, int tid_in) {
;     ...
;         const int b = bid >> 5, g = 4 * (bid & 7) + ((bid >> 3) & 3);
;         LAS unsigned* wl = (LAS unsigned*)(lds + wave * 8704);
;         LAS float* carry = (LAS float*)(lds + 8 * 8704);
;         const float lr = lbp[(g * 64 + lane) * 2], li = lbp[(g * 64 + lane) * 2 + 1];
;     ...
;         const int R0 = (bid * NWAVES + wave) * 8, c0 = 8 * lane;
;         float w0[8], w1[8], w2[8], bb[8];
; #pragma unroll
;         for (int j = 0; j < 8; ++j) { w0[j] = cw[c0 + j]; w1[j] = cw[512 + c0 + j]; w2[j] = cw[1024 + c0 + j]; bb[j] = cb[c0 + j]; }
;         float vm2[8], vm1[8];
; #pragma unroll
;         for (int j = 0; j < 8; ++j) { vm2[j] = 0.f; vm1[j] = 0.f; }
;         if ((R0 & (SEQ - 1)) != 0) {
;             const u32x4 c2 = *(const u32x4*)(z + (size_t)(R0 - 2) * INC + 512 + c0), v2 = *(const u32x4*)(z + (size_t)(R0 - 2) * INC + 1024 + c0);
;             const u32x4 c1 = *(const u32x4*)(z + (size_t)(R0 - 1) * INC + 512 + c0), v1 = *(const u32x4*)(z + (size_t)(R0 - 1) * INC + 1024 + c0);
; #pragma unroll
;             for (int q = 0; q < 4; ++q) {
;                 vm2[2 * q] = bflo(c2[q]) * bflo(v2[q]); vm2[2 * q + 1] = bfhi(c2[q]) * bfhi(v2[q]);
;                 vm1[2 * q] = bflo(c1[q]) * bflo(v1[q]); vm1[2 * q + 1] = bfhi(c1[q]) * bfhi(v1[q]);
;             }
;         }
.LBB0_638:
	s_or_b64 exec, exec, s[0:1]
	v_readlane_b32 s8, v254, 6
	v_readlane_b32 s9, v254, 7
	s_mov_b64 s[0:1], s[40:41]
	s_and_b64 vcc, exec, s[8:9]
	s_waitcnt lgkmcnt(0)
	s_barrier
	s_cbranch_vccz .LBB0_676
	s_load_dwordx2 s[12:13], s[0:1], 0x100
	s_load_dwordx2 s[16:17], s[0:1], 0x80
	s_load_dwordx4 s[24:27], s[0:1], 0x40
	v_readlane_b32 s0, v254, 20
	v_readlane_b32 s14, v255, 15
	s_waitcnt lgkmcnt(0)
	s_add_u32 s20, s12, s0
	v_readlane_b32 s0, v254, 22
	s_addc_u32 s28, s13, s0
	s_add_u32 s0, s12, 0x12b94000
	s_addc_u32 s1, s13, 0
	s_add_u32 s8, s12, 0x17b94400
	s_addc_u32 s9, s13, 0
	s_add_u32 s10, s20, 0x2a00000
	s_addc_u32 s11, s28, 0
	s_add_u32 s78, s20, 0x2a04000
	s_addc_u32 s79, s28, 0
	s_add_u32 s94, s20, 0x2a24000
	s_addc_u32 s95, s28, 0
	v_readlane_b32 s20, v254, 4
	v_readlane_b32 s21, v254, 5
	s_add_u32 s31, s16, s20
	s_addc_u32 s48, s17, s21
	s_add_u32 s46, s24, s14
	v_readlane_b32 s14, v255, 14
	s_addc_u32 s47, s25, s14
	s_add_u32 s70, s26, s20
	s_addc_u32 s71, s27, s21
	s_add_u32 s16, s12, 0x16b94000
	v_readlane_b32 s30, v255, 7
	s_addc_u32 s17, s13, 0
	s_mov_b32 s49, s2
	s_cmp_eq_u32 s98, 0
	s_cbranch_scc1 .Lmix_noperm
	s_and_b32 s49, s2, 7
	s_lshl_b32 s49, s49, 5
	s_bfe_u32 s99, s2, 0x20003
	s_lshl_b32 s99, s99, 3
	s_or_b32 s49, s49, s99
	s_lshr_b32 s99, s2, 5
	s_or_b32 s49, s49, s99
	s_lshl_b32 s30, s49, 2
.Lmix_noperm:
	s_branch .LBB0_643
.LBB0_640:
	v_lshlrev_b32_e32 v0, 5, v82
	v_lshl_add_u64 v[2:3], s[46:47], 0, v[0:1]
	s_mov_b64 s[12:13], 0x1000
	v_lshl_add_u64 v[4:5], v[2:3], 0, s[12:13]
	v_add_co_u32_e32 v2, vcc, 0x1000, v2
	global_load_dwordx4 v[18:21], v0, s[46:47] offset:2064
	global_load_dwordx4 v[22:25], v0, s[46:47] offset:2048
	v_addc_co_u32_e32 v3, vcc, 0, v3, vcc
	global_load_dwordx4 v[14:17], v[2:3], off
	global_load_dwordx4 v[10:13], v[4:5], off offset:16
	global_load_dwordx4 v[50:53], v0, s[46:47] offset:16
	global_load_dwordx4 v[54:57], v0, s[46:47]
	s_nop 0
	global_load_dwordx4 v[2:5], v0, s[70:71] offset:16
	global_load_dwordx4 v[6:9], v0, s[70:71]
	s_lshl_b32 s12, s49, 6
	s_lshl_b32 s13, s20, 3
	s_add_i32 s56, s13, s12
	v_lshlrev_b32_e32 v0, 3, v82
	s_and_b32 s12, s56, 0x7f8
	s_cmp_lg_u32 s12, 0
	v_lshlrev_b32_e32 v0, 1, v0
	s_cbranch_scc0 .LBB0_668
	s_ashr_i32 s57, s56, 31
	s_lshl_b64 s[12:13], s[56:57], 12
	s_add_u32 s12, s0, s12
	s_addc_u32 s13, s1, s13
	s_movk_i32 s24, 0xe000
	v_lshl_add_u64 v[26:27], s[12:13], 0, v[0:1]
	s_mov_b32 s25, -1
	v_lshl_add_u64 v[26:27], v[26:27], 0, s[24:25]
	global_load_dwordx4 v[28:31], v[26:27], off offset:1024
	global_load_dwordx4 v[32:35], v[26:27], off offset:2048
	global_load_dwordx4 v[36:39], v0, s[12:13] offset:-3072
	global_load_dwordx4 v[40:43], v0, s[12:13] offset:-2048
	s_waitcnt vmcnt(3)
	v_lshlrev_b32_e32 v26, 16, v28
	v_and_b32_e32 v27, 0xffff0000, v28
	s_waitcnt vmcnt(2)
	v_lshlrev_b32_e32 v44, 16, v32
	v_and_b32_e32 v45, 0xffff0000, v32
	v_lshlrev_b32_e32 v28, 16, v29
	v_and_b32_e32 v29, 0xffff0000, v29
	v_lshlrev_b32_e32 v32, 16, v33
	v_and_b32_e32 v33, 0xffff0000, v33
	v_pk_mul_f32 v[26:27], v[26:27], v[44:45]
	s_waitcnt vmcnt(1)
	v_lshlrev_b32_e32 v44, 16, v36
	v_and_b32_e32 v45, 0xffff0000, v36
	v_pk_mul_f32 v[28:29], v[28:29], v[32:33]
	v_lshlrev_b32_e32 v32, 16, v37
	v_and_b32_e32 v33, 0xffff0000, v37
	s_waitcnt vmcnt(0)
	v_lshlrev_b32_e32 v36, 16, v41
	v_and_b32_e32 v37, 0xffff0000, v41
	v_pk_mul_f32 v[134:135], v[32:33], v[36:37]
	v_lshlrev_b32_e32 v32, 16, v30
	v_and_b32_e32 v33, 0xffff0000, v30
	v_lshlrev_b32_e32 v36, 16, v34
	v_and_b32_e32 v37, 0xffff0000, v34
	v_lshlrev_b32_e32 v46, 16, v40
	v_and_b32_e32 v47, 0xffff0000, v40
	v_pk_mul_f32 v[32:33], v[32:33], v[36:37]
	v_lshlrev_b32_e32 v36, 16, v38
	v_and_b32_e32 v37, 0xffff0000, v38
	v_lshlrev_b32_e32 v40, 16, v42
	v_and_b32_e32 v41, 0xffff0000, v42
	v_lshlrev_b32_e32 v30, 16, v31
	v_and_b32_e32 v31, 0xffff0000, v31
	v_lshlrev_b32_e32 v34, 16, v35
	v_and_b32_e32 v35, 0xffff0000, v35
	v_pk_mul_f32 v[106:107], v[36:37], v[40:41]
	v_pk_mul_f32 v[30:31], v[30:31], v[34:35]
	v_lshlrev_b32_e32 v34, 16, v39
	v_and_b32_e32 v35, 0xffff0000, v39
	v_lshlrev_b32_e32 v36, 16, v43
	v_and_b32_e32 v37, 0xffff0000, v43
	v_pk_mul_f32 v[122:123], v[44:45], v[46:47]
	v_pk_mul_f32 v[108:109], v[34:35], v[36:37]
	v_mov_b32_e32 v142, v123
	v_mov_b32_e32 v144, v135
	v_mov_b32_e32 v136, v107
	v_mov_b32_e32 v138, v109
	v_mov_b32_e32 v123, v26
	v_mov_b32_e32 v143, v27
	v_mov_b32_e32 v135, v28
	v_mov_b32_e32 v145, v29
	v_mov_b32_e32 v107, v32
	v_mov_b32_e32 v137, v33
	v_mov_b32_e32 v109, v30
	v_mov_b32_e32 v139, v31
